# odd_prep loop software-pipelined: next token's row + k_pe/rope loads issued before processing the current token (on top of v53)
# baseline (speedup 1.0000x reference)
.LBB0_360:
	v_readlane_b32 s0, v252, 38
	v_readlane_b32 s1, v252, 39
	v_mov_b32_e32 v0, v167
	s_andn2_b64 vcc, exec, s[0:1]
	s_cbranch_vccnz .LBB0_367
	v_and_b32_e32 v6, 63, v0
	v_lshlrev_b32_e32 v0, 3, v6
	v_lshlrev_b32_e32 v4, 2, v6
	v_mov_b32_e32 v5, v1
	v_readlane_b32 s2, v252, 40
	v_cmp_eq_u32_e64 s[0:1], 0, v6
	v_cmp_gt_u32_e64 s[6:7], 32, v6
	v_lshl_add_u64 v[2:3], s[20:21], 0, v[0:1]
	v_lshl_add_u64 v[4:5], s[18:19], 0, v[4:5]
	v_lshlrev_b32_e32 v10, 1, v0
	v_lshlrev_b32_e32 v0, 1, v6
	s_mov_b32 s40, s2
	s_ashr_i32 s41, s40, 31
	s_mul_i32 s10, s40, 0x1a00
	s_mul_hi_i32 s2, s40, 0x1a00
	s_add_u32 s42, s22, s10
	s_addc_u32 s43, s23, s2
	s_waitcnt lgkmcnt(0)
	global_load_dwordx4 v[32:35], v10, s[42:43]
	global_load_dwordx4 v[36:39], v10, s[42:43] offset:1024
	s_mov_b64 s[54:55], exec
	s_and_b64 exec, exec, s[6:7]
	v_lshl_add_u64 v[28:29], s[42:43], 0, v[0:1]
	v_add_co_u32_e32 v28, vcc, 0x1000, v28
	s_lshl_b64 s[24:25], s[40:41], 8
	s_nop 0
	v_addc_co_u32_e32 v29, vcc, 0, v29, vcc
	v_lshl_add_u64 v[30:31], v[2:3], 0, s[24:25]
	global_load_ushort v40, v[28:29], off offset:2048
	global_load_ushort v41, v[28:29], off offset:2112
	s_nop 0
	global_load_dwordx2 v[42:43], v[30:31], off
	s_mov_b64 exec, s[54:55]
	s_branch .LBB0_363

.LBB0_363:
	s_ashr_i32 s41, s40, 31
	s_waitcnt vmcnt(0) lgkmcnt(0)
	v_mov_b32_e32 v6, v32
	v_mov_b32_e32 v7, v33
	v_mov_b32_e32 v8, v34
	v_mov_b32_e32 v9, v35
	v_mov_b32_e32 v12, v36
	v_mov_b32_e32 v13, v37
	v_mov_b32_e32 v14, v38
	v_mov_b32_e32 v15, v39
	v_mov_b32_e32 v24, v40
	v_mov_b32_e32 v25, v41
	v_mov_b32_e32 v26, v42
	v_mov_b32_e32 v27, v43
	v_readlane_b32 s2, v250, 56
	s_nop 0
	s_add_i32 s26, s40, s2
	s_cmpk_lt_i32 s26, 0x4000
	s_cbranch_scc0 .Loddprep_nopf
	s_ashr_i32 s27, s26, 31
	s_mul_i32 s10, s26, 0x1a00
	s_mul_hi_i32 s2, s26, 0x1a00
	s_add_u32 s42, s22, s10
	s_addc_u32 s43, s23, s2
	global_load_dwordx4 v[32:35], v10, s[42:43]
	global_load_dwordx4 v[36:39], v10, s[42:43] offset:1024
	s_mov_b64 s[54:55], exec
	s_and_b64 exec, exec, s[6:7]
	v_lshl_add_u64 v[28:29], s[42:43], 0, v[0:1]
	v_add_co_u32_e32 v28, vcc, 0x1000, v28
	s_lshl_b64 s[24:25], s[26:27], 8
	s_nop 0
	v_addc_co_u32_e32 v29, vcc, 0, v29, vcc
	v_lshl_add_u64 v[30:31], v[2:3], 0, s[24:25]
	global_load_ushort v40, v[28:29], off offset:2048
	global_load_ushort v41, v[28:29], off offset:2112
	s_nop 0
	global_load_dwordx2 v[42:43], v[30:31], off
	s_mov_b64 exec, s[54:55]
.Loddprep_nopf:
	v_and_b32_e32 v21, 0xffff0000, v6
	v_and_b32_e32 v20, 0xffff0000, v12
	v_lshlrev_b32_e32 v19, 16, v6
	v_lshlrev_b32_e32 v18, 16, v12
	v_pk_mul_f32 v[20:21], v[20:21], v[20:21]
	v_lshlrev_b32_e32 v23, 16, v7
	v_lshlrev_b32_e32 v22, 16, v13
	v_pk_fma_f32 v[18:19], v[18:19], v[18:19], v[20:21]
	v_and_b32_e32 v7, 0xffff0000, v7
	v_and_b32_e32 v6, 0xffff0000, v13
	v_pk_fma_f32 v[18:19], v[22:23], v[22:23], v[18:19]
	v_lshlrev_b32_e32 v13, 16, v8
	v_lshlrev_b32_e32 v12, 16, v14
	v_pk_fma_f32 v[6:7], v[6:7], v[6:7], v[18:19]
	v_and_b32_e32 v17, 0xffff0000, v9
	v_pk_fma_f32 v[6:7], v[12:13], v[12:13], v[6:7]
	v_and_b32_e32 v13, 0xffff0000, v8
	v_and_b32_e32 v12, 0xffff0000, v14
	v_lshlrev_b32_e32 v9, 16, v9
	v_lshlrev_b32_e32 v8, 16, v15
	v_pk_fma_f32 v[6:7], v[12:13], v[12:13], v[6:7]
	v_and_b32_e32 v16, 0xffff0000, v15
	v_pk_fma_f32 v[6:7], v[8:9], v[8:9], v[6:7]
	s_nop 0
	v_pk_fma_f32 v[6:7], v[16:17], v[16:17], v[6:7]
	s_nop 1
	v_mov_b32_dpp v9, v7 quad_perm:[1,0,3,2] row_mask:0xf bank_mask:0xf bound_ctrl:1
	v_mov_b32_dpp v8, v6 quad_perm:[1,0,3,2] row_mask:0xf bank_mask:0xf bound_ctrl:1
	v_pk_add_f32 v[6:7], v[6:7], v[8:9]
	s_nop 1
	v_mov_b32_dpp v9, v7 quad_perm:[2,3,0,1] row_mask:0xf bank_mask:0xf bound_ctrl:1
	v_mov_b32_dpp v8, v6 quad_perm:[2,3,0,1] row_mask:0xf bank_mask:0xf bound_ctrl:1
	v_pk_add_f32 v[6:7], v[6:7], v[8:9]
	s_nop 1
	v_mov_b32_dpp v9, v7 row_ror:4 row_mask:0xf bank_mask:0xf bound_ctrl:1
	v_mov_b32_dpp v8, v6 row_ror:4 row_mask:0xf bank_mask:0xf bound_ctrl:1
	v_pk_add_f32 v[6:7], v[6:7], v[8:9]
	s_nop 1
	v_mov_b32_dpp v9, v7 row_ror:8 row_mask:0xf bank_mask:0xf bound_ctrl:1
	v_mov_b32_dpp v8, v6 row_ror:8 row_mask:0xf bank_mask:0xf bound_ctrl:1
	v_pk_add_f32 v[6:7], v[6:7], v[8:9]
	ds_bpermute_b32 v9, v207, v7
	ds_bpermute_b32 v8, v207, v6
	s_waitcnt lgkmcnt(0)
	v_pk_add_f32 v[6:7], v[6:7], v[8:9]
	ds_bpermute_b32 v9, v209, v7
	ds_bpermute_b32 v8, v209, v6
	s_and_saveexec_b64 s[54:55], s[0:1]
	s_cbranch_execz .LBB0_365
	s_waitcnt lgkmcnt(0)
	v_pk_add_f32 v[6:7], v[6:7], v[8:9]
	s_mov_b32 s2, 0x3b000000
	v_pk_fma_f32 v[6:7], v[6:7], s[2:3], v[166:167] op_sel_hi:[1,0,0]
	s_mov_b32 s2, 0x800000
	v_mul_f32_e32 v8, 0x4b800000, v7
	v_cmp_gt_f32_e32 vcc, s2, v7
	v_cmp_gt_f32_e64 s[10:11], s2, v6
	s_lshl_b64 s[24:25], s[40:41], 2
	v_cndmask_b32_e32 v7, v7, v8, vcc
	v_rsq_f32_e32 v7, v7
	v_mul_f32_e32 v8, 0x4b800000, v6
	v_cndmask_b32_e64 v6, v6, v8, s[10:11]
	v_rsq_f32_e32 v6, v6
	s_add_u32 s26, s50, s24
	v_mul_f32_e32 v8, 0x45800000, v7
	s_addc_u32 s27, s51, s25
	v_cndmask_b32_e32 v7, v7, v8, vcc
	global_store_dword v1, v7, s[26:27]
	v_mul_f32_e32 v7, 0x45800000, v6
	v_cndmask_b32_e64 v6, v6, v7, s[10:11]
	s_add_u32 s10, s38, s24
	s_addc_u32 s11, s39, s25
	global_store_dword v1, v6, s[10:11]
